# far-tile fast path + phase-4 order split with the GEMM main-loop heads pinned (p2align + nops) to the byte phases they have in the previous best build
# speedup vs baseline: 1.0016x; 1.0016x over previous
;     __device__ __forceinline__ bool next(int i, Unit& u) const { return static_next((long)i * G + c, nM, nN, u); }
;     __device__ __forceinline__ const char* aptr(const Unit& u) const { return (const char*)(A + (size_t)u.pm * 256 * K); }
;     __device__ __forceinline__ const char* bptr(const Unit& u) const { return (const char*)(B + (size_t)u.pn * 256 * K); }
;     __device__ __forceinline__ bool next(int i, Unit& u) const { if (i > 0 || c >= 32) return false; u.z = c >> 4; u.pm = c & 15; u.pn = 0; return true; }
;     __device__ __forceinline__ const char* aptr(const Unit& u) const { return (const char*)(A0 + ((size_t)u.z * 4096 + (size_t)u.pm * 256) * 2048); }
;     __device__ __forceinline__ const char* bptr(const Unit& u) const { return (const char*)(W1T + (size_t)u.z * 256 * 2048); }
;     __device__ __forceinline__ bool next(int i, Unit& u) const { const bool ok = static_next((long)(i >> 2) * G + c, 64, 8, u); u.z = i & 3; return ok; }
;     __device__ __forceinline__ const char* aptr(const Unit& u) const { return (const char*)(O + ((size_t)u.z * MT + (size_t)u.pm * 256) * DBR); }
;     __device__ __forceinline__ const char* bptr(const Unit& u) const { return (const char*)(WBR + ((size_t)u.z * DM + (size_t)u.pn * 256) * DBR); }
; template <class Epi, class Sched>
; __device__ __forceinline__ void gemm_phase(LAS unsigned char* lds, const int K, const Sched& S, const Epi& E) {
;     ...
;     f32x4 acc[2][2][4][2];
; #pragma unroll
;     for (int a = 0; a < 2; ++a)
; #pragma unroll
;         for (int b = 0; b < 2; ++b)
; #pragma unroll
;             for (int m = 0; m < 4; ++m)
; #pragma unroll
;                 for (int n = 0; n < 2; ++n) acc[a][b][m][n] = (f32x4){0.f, 0.f, 0.f, 0.f};
;     bf16x8 At[4][2], B0[2][2], B1[2][2];
;     const char* cA = S.aptr(cur); const char* cB = S.bptr(cur);
;     PG8_STAGE(PG8_SB(0, 0), cB, voffB); PG8_STAGE(PG8_SB(0, 1), cB + hstep, voffB); PG8_STAGE(PG8_SA(0, 0), cA, voffA); PG8_STAGE(PG8_SA(0, 1), cA + hstep, voffA);
;     if (wr == 1) PG8_BAR;
;     PG8_WAIT_V(2); PG8_BAR;
;     PG8_STAGE(PG8_SB(1, 0), cB + kstep, voffB); PG8_STAGE(PG8_SA(1, 0), cA + kstep, voffA); PG8_STAGE(PG8_SB(1, 1), cB + hstep + kstep, voffB);
;     PG8_WAIT_V(6); PG8_BAR;
;     for (;;) {
;         const bool has_next = S.next(ui + 1, nxt);
;         const char* nA = has_next ? S.aptr(nxt) : cA; const char* nB = has_next ? S.bptr(nxt) : cB;
.LBB0_781:
	v_lshrrev_b32_e32 v18, 1, v13
	v_and_b32_e32 v141, 24, v18
	s_lshl_b32 s6, s6, 5
	v_and_b32_e32 v17, 15, v13
	v_lshlrev_b32_e32 v18, 1, v141
	v_lshlrev_b32_e32 v13, 2, v13
	s_and_b32 s20, s6, 0x60
	s_add_i32 m0, s16, 0x18000
	v_lshl_add_u64 v[8:9], v[8:9], 0, s[52:53]
	v_lshl_or_b32 v140, s7, 6, v17
	v_lshl_or_b32 v17, v17, 6, v18
	s_lshl_b32 s7, s7, 13
	v_and_b32_e32 v13, 32, v13
	s_lshl_b32 s6, s20, 7
	s_waitcnt vmcnt(2)
	s_barrier
	global_load_lds_dwordx4 v[8:9], off
	v_lshl_add_u64 v[6:7], v[6:7], 0, s[52:53]
	s_add_i32 m0, s16, 0x1a000
	s_add_i32 s21, s16, 0x8000
	s_add_i32 s24, s16, 0xa000
	v_bitop3_b32 v142, v17, s6, v13 bitop3:0xde
	global_load_lds_dwordx4 v[6:7], off
	v_lshl_add_u64 v[4:5], v[4:5], 0, s[52:53]
	s_mov_b32 m0, s21
	s_add_u32 s6, s0, 0x80080
	v_bitop3_b32 v18, v17, s7, v13 bitop3:0xde
	global_load_lds_dwordx4 v[4:5], off
	v_lshl_add_u64 v[2:3], v[2:3], 0, s[52:53]
	s_mov_b32 m0, s24
	s_addc_u32 s7, s1, 0
	global_load_lds_dwordx4 v[2:3], off
	s_add_i32 m0, s16, 0x1c000
	v_lshl_add_u64 v[2:3], s[6:7], 0, v[0:1]
	global_load_lds_dwordx4 v[2:3], off
	v_lshl_add_u64 v[2:3], s[6:7], 0, v[130:131]
	s_add_i32 m0, s16, 0x1e000
	v_readlane_b32 s6, v254, 2
	global_load_lds_dwordx4 v[2:3], off
	v_lshlrev_b32_e32 v2, 15, v15
	s_add_u32 s25, s68, s6
	v_readlane_b32 s6, v254, 47
	v_and_b32_e32 v2, 0xffff0000, v2
	s_addc_u32 s26, s69, s6
	v_readlane_b32 s6, v254, 3
	v_lshl_add_u32 v2, v14, 12, v2
	v_and_b32_e32 v3, 1, v15
	s_add_u32 s6, s68, s6
	v_readlane_b32 s7, v254, 4
	v_lshl_or_b32 v2, v3, 6, v2
	s_addc_u32 s7, s69, s7
	v_lshl_add_u32 v2, v16, 1, v2
	v_mov_b32_e32 v3, v1
	v_lshl_add_u64 v[136:137], s[6:7], 0, v[2:3]
	v_lshlrev_b32_e32 v2, 15, v10
	v_and_b32_e32 v2, 0xffff0000, v2
	v_lshl_add_u32 v2, v11, 12, v2
	v_and_b32_e32 v3, 1, v10
	v_lshl_or_b32 v2, v3, 6, v2
	v_lshl_add_u32 v2, v12, 1, v2
	v_mov_b32_e32 v3, v1
	s_waitcnt vmcnt(6)
	v_lshl_add_u64 v[138:139], s[6:7], 0, v[2:3]
	v_readlane_b32 s6, v254, 5
	s_add_u32 s27, s68, s6
	v_readlane_b32 s6, v254, 8
	v_mov_b32_e32 v2, 0
	s_addc_u32 s28, s69, s6
	s_mov_b32 s29, -2
	s_mov_b64 s[6:7], 0
	v_add_u32_e32 v143, 0, v18
	v_mov_b32_e32 v3, v2
	v_mov_b32_e32 v4, v2
	v_mov_b32_e32 v5, v2
	v_mov_b32_e32 v6, v2
	v_mov_b32_e32 v7, v2
	v_mov_b32_e32 v8, v2
	v_mov_b32_e32 v9, v2
	v_mov_b32_e32 v18, v2
	v_mov_b32_e32 v19, v2
	v_mov_b32_e32 v20, v2
	v_mov_b32_e32 v21, v2
	v_mov_b32_e32 v22, v2
	v_mov_b32_e32 v23, v2
	v_mov_b32_e32 v24, v2
	v_mov_b32_e32 v25, v2
	v_mov_b32_e32 v34, v2
	v_mov_b32_e32 v35, v2
	v_mov_b32_e32 v36, v2
	v_mov_b32_e32 v37, v2
	v_mov_b32_e32 v38, v2
	v_mov_b32_e32 v39, v2
	v_mov_b32_e32 v40, v2
	v_mov_b32_e32 v41, v2
	v_mov_b32_e32 v50, v2
	v_mov_b32_e32 v51, v2
	v_mov_b32_e32 v52, v2
	v_mov_b32_e32 v53, v2
	v_mov_b32_e32 v54, v2
	v_mov_b32_e32 v55, v2
	v_mov_b32_e32 v56, v2
	v_mov_b32_e32 v57, v2
	v_mov_b32_e32 v10, v2
	v_mov_b32_e32 v11, v2
	v_mov_b32_e32 v12, v2
	v_mov_b32_e32 v13, v2
	v_mov_b32_e32 v14, v2
	v_mov_b32_e32 v15, v2
	v_mov_b32_e32 v16, v2
	v_mov_b32_e32 v17, v2
	v_mov_b32_e32 v26, v2
	v_mov_b32_e32 v27, v2
	v_mov_b32_e32 v28, v2
	v_mov_b32_e32 v29, v2
	v_mov_b32_e32 v30, v2
	v_mov_b32_e32 v31, v2
	v_mov_b32_e32 v32, v2
	v_mov_b32_e32 v33, v2
	v_mov_b32_e32 v42, v2
	v_mov_b32_e32 v43, v2
	v_mov_b32_e32 v44, v2
	v_mov_b32_e32 v45, v2
	v_mov_b32_e32 v46, v2
	v_mov_b32_e32 v47, v2
	v_mov_b32_e32 v48, v2
	v_mov_b32_e32 v49, v2
	v_mov_b32_e32 v58, v2
	v_mov_b32_e32 v59, v2
	v_mov_b32_e32 v60, v2
	v_mov_b32_e32 v61, v2
	v_mov_b32_e32 v62, v2
	v_mov_b32_e32 v63, v2
	v_mov_b32_e32 v64, v2
	v_mov_b32_e32 v65, v2
	v_mov_b32_e32 v66, v2
	v_mov_b32_e32 v67, v2
	v_mov_b32_e32 v68, v2
	v_mov_b32_e32 v69, v2
	v_mov_b32_e32 v70, v2
	v_mov_b32_e32 v71, v2
	v_mov_b32_e32 v72, v2
	v_mov_b32_e32 v73, v2
	v_mov_b32_e32 v82, v2
	v_mov_b32_e32 v83, v2
	v_mov_b32_e32 v84, v2
	v_mov_b32_e32 v85, v2
	v_mov_b32_e32 v86, v2
	v_mov_b32_e32 v87, v2
	v_mov_b32_e32 v88, v2
	v_mov_b32_e32 v89, v2
	v_mov_b32_e32 v98, v2
	v_mov_b32_e32 v99, v2
	v_mov_b32_e32 v100, v2
	v_mov_b32_e32 v101, v2
	v_mov_b32_e32 v102, v2
	v_mov_b32_e32 v103, v2
	v_mov_b32_e32 v104, v2
	v_mov_b32_e32 v105, v2
	v_mov_b32_e32 v114, v2
	v_mov_b32_e32 v115, v2
	v_mov_b32_e32 v116, v2
	v_mov_b32_e32 v117, v2
	v_mov_b32_e32 v118, v2
	v_mov_b32_e32 v119, v2
	v_mov_b32_e32 v120, v2
	v_mov_b32_e32 v121, v2
	v_mov_b32_e32 v74, v2
	v_mov_b32_e32 v75, v2
	v_mov_b32_e32 v76, v2
	v_mov_b32_e32 v77, v2
	v_mov_b32_e32 v78, v2
	v_mov_b32_e32 v79, v2
	v_mov_b32_e32 v80, v2
	v_mov_b32_e32 v81, v2
	v_mov_b32_e32 v90, v2
	v_mov_b32_e32 v91, v2
	v_mov_b32_e32 v92, v2
	v_mov_b32_e32 v93, v2
	v_mov_b32_e32 v94, v2
	v_mov_b32_e32 v95, v2
	v_mov_b32_e32 v96, v2
	v_mov_b32_e32 v97, v2
	v_mov_b32_e32 v106, v2
	v_mov_b32_e32 v107, v2
	v_mov_b32_e32 v108, v2
	v_mov_b32_e32 v109, v2
	v_mov_b32_e32 v110, v2
	v_mov_b32_e32 v111, v2
	v_mov_b32_e32 v112, v2
	v_mov_b32_e32 v113, v2
	v_mov_b32_e32 v122, v2
	v_mov_b32_e32 v123, v2
	v_mov_b32_e32 v124, v2
	v_mov_b32_e32 v125, v2
	v_mov_b32_e32 v126, v2
	v_mov_b32_e32 v127, v2
	v_mov_b32_e32 v128, v2
	v_mov_b32_e32 v129, v2
	s_barrier
	.p2align	6
	s_nop 0
	s_nop 0
	s_nop 0
	s_nop 0
	s_nop 0
	s_nop 0
	s_nop 0

;     __device__ __forceinline__ bool next(int i, Unit& u) const { return static_next((long)i * G + c, nM, nN, u); }
;     __device__ __forceinline__ const char* aptr(const Unit& u) const { return (const char*)(A + (size_t)u.pm * 256 * K); }
;     __device__ __forceinline__ const char* bptr(const Unit& u) const { return (const char*)(B + (size_t)u.pn * 256 * K); }
;     __device__ __forceinline__ bool next(int i, Unit& u) const { if (i > 0 || c >= 32) return false; u.z = c >> 4; u.pm = c & 15; u.pn = 0; return true; }
;     __device__ __forceinline__ const char* aptr(const Unit& u) const { return (const char*)(A0 + ((size_t)u.z * 4096 + (size_t)u.pm * 256) * 2048); }
;     __device__ __forceinline__ const char* bptr(const Unit& u) const { return (const char*)(W1T + (size_t)u.z * 256 * 2048); }
;     __device__ __forceinline__ bool next(int i, Unit& u) const { const bool ok = static_next((long)(i >> 2) * G + c, 64, 8, u); u.z = i & 3; return ok; }
;     __device__ __forceinline__ const char* aptr(const Unit& u) const { return (const char*)(O + ((size_t)u.z * MT + (size_t)u.pm * 256) * DBR); }
;     __device__ __forceinline__ const char* bptr(const Unit& u) const { return (const char*)(WBR + ((size_t)u.z * DM + (size_t)u.pn * 256) * DBR); }
;     __device__ __forceinline__ const char* aptr(const Unit& u) const { return (const char*)(A + (size_t)u.pm * 256 * DM); }
; template <class Epi, class Sched>
; __device__ __forceinline__ void gemm_phase(LAS unsigned char* lds, const int K, const Sched& S, const Epi& E) {
;     ...
;         const bool has_next = S.next(ui + 1, nxt);
;         const char* nA = has_next ? S.aptr(nxt) : cA; const char* nB = has_next ? S.bptr(nxt) : cB;
;         for (int t = 0; t < nt; t += 2) {
;             const bool last = (t == nt - 2);
;             const char* a1 = cA + (size_t)(t + 1) * kstep;
;             const char* a2 = last ? nA : cA + (size_t)(t + 2) * kstep; const char* b2 = last ? nB : cB + (size_t)(t + 2) * kstep;
;             const char* a3 = a2 + kstep; const char* b3 = b2 + kstep;
;     ...
; #pragma unroll
;         for (int a = 0; a < 2; ++a)
; #pragma unroll
;             for (int b = 0; b < 2; ++b)
; #pragma unroll
;                 for (int m = 0; m < 4; ++m)
; #pragma unroll
;                     for (int n = 0; n < 2; ++n) acc[a][b][m][n] = (f32x4){0.f, 0.f, 0.f, 0.f};
;         cur = nxt; cA = nA; cB = nB; ++ui;
.LBB0_919:
	s_ashr_i32 s17, s16, 31
	s_lshl_b64 s[18:19], s[16:17], 20
	s_add_u32 s18, s26, s18
	s_addc_u32 s19, s27, s19
	s_and_b64 s[20:21], s[6:7], exec
	s_cselect_b32 s17, s19, s5
	s_cselect_b32 s71, s18, s4
	s_ashr_i32 s15, s14, 31
	s_lshl_b64 s[20:21], s[14:15], 20
	s_add_u32 s20, s28, s20
	s_addc_u32 s21, s29, s21
	s_and_b64 s[24:25], s[6:7], exec
	s_cselect_b32 s15, s21, s9
	s_cselect_b32 s76, s20, s8
	s_add_u32 s4, s4, 0x80080
	s_addc_u32 s5, s5, 0
	s_add_u32 s77, s8, 0x100
	v_mov_b32_e32 v2, 0
	s_addc_u32 s82, s9, 0
	s_mov_b32 s83, -2
	v_mov_b32_e32 v3, v2
	v_mov_b32_e32 v4, v2
	v_mov_b32_e32 v5, v2
	v_mov_b32_e32 v6, v2
	v_mov_b32_e32 v7, v2
	v_mov_b32_e32 v8, v2
	v_mov_b32_e32 v9, v2
	v_mov_b32_e32 v18, v2
	v_mov_b32_e32 v19, v2
	v_mov_b32_e32 v20, v2
	v_mov_b32_e32 v21, v2
	v_mov_b32_e32 v22, v2
	v_mov_b32_e32 v23, v2
	v_mov_b32_e32 v24, v2
	v_mov_b32_e32 v25, v2
	v_mov_b32_e32 v34, v2
	v_mov_b32_e32 v35, v2
	v_mov_b32_e32 v36, v2
	v_mov_b32_e32 v37, v2
	v_mov_b32_e32 v38, v2
	v_mov_b32_e32 v39, v2
	v_mov_b32_e32 v40, v2
	v_mov_b32_e32 v41, v2
	v_mov_b32_e32 v50, v2
	v_mov_b32_e32 v51, v2
	v_mov_b32_e32 v52, v2
	v_mov_b32_e32 v53, v2
	v_mov_b32_e32 v54, v2
	v_mov_b32_e32 v55, v2
	v_mov_b32_e32 v56, v2
	v_mov_b32_e32 v57, v2
	v_mov_b32_e32 v10, v2
	v_mov_b32_e32 v11, v2
	v_mov_b32_e32 v12, v2
	v_mov_b32_e32 v13, v2
	v_mov_b32_e32 v14, v2
	v_mov_b32_e32 v15, v2
	v_mov_b32_e32 v16, v2
	v_mov_b32_e32 v17, v2
	v_mov_b32_e32 v26, v2
	v_mov_b32_e32 v27, v2
	v_mov_b32_e32 v28, v2
	v_mov_b32_e32 v29, v2
	v_mov_b32_e32 v30, v2
	v_mov_b32_e32 v31, v2
	v_mov_b32_e32 v32, v2
	v_mov_b32_e32 v33, v2
	v_mov_b32_e32 v42, v2
	v_mov_b32_e32 v43, v2
	v_mov_b32_e32 v44, v2
	v_mov_b32_e32 v45, v2
	v_mov_b32_e32 v46, v2
	v_mov_b32_e32 v47, v2
	v_mov_b32_e32 v48, v2
	v_mov_b32_e32 v49, v2
	v_mov_b32_e32 v58, v2
	v_mov_b32_e32 v59, v2
	v_mov_b32_e32 v60, v2
	v_mov_b32_e32 v61, v2
	v_mov_b32_e32 v62, v2
	v_mov_b32_e32 v63, v2
	v_mov_b32_e32 v64, v2
	v_mov_b32_e32 v65, v2
	v_mov_b32_e32 v66, v2
	v_mov_b32_e32 v67, v2
	v_mov_b32_e32 v68, v2
	v_mov_b32_e32 v69, v2
	v_mov_b32_e32 v70, v2
	v_mov_b32_e32 v71, v2
	v_mov_b32_e32 v72, v2
	v_mov_b32_e32 v73, v2
	v_mov_b32_e32 v82, v2
	v_mov_b32_e32 v83, v2
	v_mov_b32_e32 v84, v2
	v_mov_b32_e32 v85, v2
	v_mov_b32_e32 v86, v2
	v_mov_b32_e32 v87, v2
	v_mov_b32_e32 v88, v2
	v_mov_b32_e32 v89, v2
	v_mov_b32_e32 v98, v2
	v_mov_b32_e32 v99, v2
	v_mov_b32_e32 v100, v2
	v_mov_b32_e32 v101, v2
	v_mov_b32_e32 v102, v2
	v_mov_b32_e32 v103, v2
	v_mov_b32_e32 v104, v2
	v_mov_b32_e32 v105, v2
	v_mov_b32_e32 v114, v2
	v_mov_b32_e32 v115, v2
	v_mov_b32_e32 v116, v2
	v_mov_b32_e32 v117, v2
	v_mov_b32_e32 v118, v2
	v_mov_b32_e32 v119, v2
	v_mov_b32_e32 v120, v2
	v_mov_b32_e32 v121, v2
	v_mov_b32_e32 v74, v2
	v_mov_b32_e32 v75, v2
	v_mov_b32_e32 v76, v2
	v_mov_b32_e32 v77, v2
	v_mov_b32_e32 v78, v2
	v_mov_b32_e32 v79, v2
	v_mov_b32_e32 v80, v2
	v_mov_b32_e32 v81, v2
	v_mov_b32_e32 v90, v2
	v_mov_b32_e32 v91, v2
	v_mov_b32_e32 v92, v2
	v_mov_b32_e32 v93, v2
	v_mov_b32_e32 v94, v2
	v_mov_b32_e32 v95, v2
	v_mov_b32_e32 v96, v2
	v_mov_b32_e32 v97, v2
	v_mov_b32_e32 v106, v2
	v_mov_b32_e32 v107, v2
	v_mov_b32_e32 v108, v2
	v_mov_b32_e32 v109, v2
	v_mov_b32_e32 v110, v2
	v_mov_b32_e32 v111, v2
	v_mov_b32_e32 v112, v2
	v_mov_b32_e32 v113, v2
	v_mov_b32_e32 v122, v2
	v_mov_b32_e32 v123, v2
	v_mov_b32_e32 v124, v2
	v_mov_b32_e32 v125, v2
	v_mov_b32_e32 v126, v2
	v_mov_b32_e32 v127, v2
	v_mov_b32_e32 v128, v2
	v_mov_b32_e32 v129, v2
	.p2align	6
	s_nop 0
	s_nop 0
	s_nop 0
	s_nop 0
	s_nop 0
	s_nop 0
	s_nop 0
	s_nop 0
	s_nop 0
	s_nop 0

;     __device__ __forceinline__ bool next(int i, Unit& u) const { return static_next((long)i * G + c, nM, nN, u); }
;     __device__ __forceinline__ const char* aptr(const Unit& u) const { return (const char*)(A + (size_t)u.pm * 256 * K); }
;     __device__ __forceinline__ const char* bptr(const Unit& u) const { return (const char*)(B + (size_t)u.pn * 256 * K); }
;     __device__ __forceinline__ bool next(int i, Unit& u) const { if (i > 0 || c >= 32) return false; u.z = c >> 4; u.pm = c & 15; u.pn = 0; return true; }
;     __device__ __forceinline__ const char* aptr(const Unit& u) const { return (const char*)(A0 + ((size_t)u.z * 4096 + (size_t)u.pm * 256) * 2048); }
;     __device__ __forceinline__ const char* bptr(const Unit& u) const { return (const char*)(W1T + (size_t)u.z * 256 * 2048); }
;     __device__ __forceinline__ bool next(int i, Unit& u) const { const bool ok = static_next((long)(i >> 2) * G + c, 64, 8, u); u.z = i & 3; return ok; }
;     __device__ __forceinline__ const char* aptr(const Unit& u) const { return (const char*)(O + ((size_t)u.z * MT + (size_t)u.pm * 256) * DBR); }
;     __device__ __forceinline__ const char* bptr(const Unit& u) const { return (const char*)(WBR + ((size_t)u.z * DM + (size_t)u.pn * 256) * DBR); }
;     __device__ __forceinline__ const char* aptr(const Unit& u) const { return (const char*)(A + (size_t)u.pm * 256 * DM); }
; template <class Epi, class Sched>
; __device__ __forceinline__ void gemm_phase(LAS unsigned char* lds, const int K, const Sched& S, const Epi& E) {
;     ...
;         const bool has_next = S.next(ui + 1, nxt);
;         const char* nA = has_next ? S.aptr(nxt) : cA; const char* nB = has_next ? S.bptr(nxt) : cB;
;         for (int t = 0; t < nt; t += 2) {
;             const bool last = (t == nt - 2);
;             const char* a1 = cA + (size_t)(t + 1) * kstep;
;             const char* a2 = last ? nA : cA + (size_t)(t + 2) * kstep; const char* b2 = last ? nB : cB + (size_t)(t + 2) * kstep;
;             const char* a3 = a2 + kstep; const char* b3 = b2 + kstep;
;     ...
; #pragma unroll
;         for (int a = 0; a < 2; ++a)
; #pragma unroll
;             for (int b = 0; b < 2; ++b)
; #pragma unroll
;                 for (int m = 0; m < 4; ++m)
; #pragma unroll
;                     for (int n = 0; n < 2; ++n) acc[a][b][m][n] = (f32x4){0.f, 0.f, 0.f, 0.f};
;         cur = nxt; cA = nA; cB = nB; ++ui;
.LBB0_997:
	s_ashr_i32 s13, s12, 31
	s_lshl_b64 s[14:15], s[12:13], 20
	s_add_u32 s14, s26, s14
	s_addc_u32 s15, s27, s15
	s_and_b64 s[16:17], s[8:9], exec
	s_cselect_b32 s13, s15, s19
	s_cselect_b32 s67, s14, s18
	s_ashr_i32 s11, s10, 31
	s_lshl_b64 s[16:17], s[10:11], 20
	s_add_u32 s16, s28, s16
	s_addc_u32 s17, s29, s17
	s_and_b64 s[24:25], s[8:9], exec
	s_cselect_b32 s11, s17, s21
	s_cselect_b32 s71, s16, s20
	s_add_u32 s18, s18, 0x80080
	s_addc_u32 s19, s19, 0
	s_add_u32 s76, s20, 0x100
	v_mov_b32_e32 v2, 0
	s_addc_u32 s77, s21, 0
	s_mov_b32 s82, -2
	v_mov_b32_e32 v3, v2
	v_mov_b32_e32 v4, v2
	v_mov_b32_e32 v5, v2
	v_mov_b32_e32 v6, v2
	v_mov_b32_e32 v7, v2
	v_mov_b32_e32 v8, v2
	v_mov_b32_e32 v9, v2
	v_mov_b32_e32 v10, v2
	v_mov_b32_e32 v11, v2
	v_mov_b32_e32 v12, v2
	v_mov_b32_e32 v13, v2
	v_mov_b32_e32 v18, v2
	v_mov_b32_e32 v19, v2
	v_mov_b32_e32 v20, v2
	v_mov_b32_e32 v21, v2
	v_mov_b32_e32 v26, v2
	v_mov_b32_e32 v27, v2
	v_mov_b32_e32 v28, v2
	v_mov_b32_e32 v29, v2
	v_mov_b32_e32 v34, v2
	v_mov_b32_e32 v35, v2
	v_mov_b32_e32 v36, v2
	v_mov_b32_e32 v37, v2
	v_mov_b32_e32 v42, v2
	v_mov_b32_e32 v43, v2
	v_mov_b32_e32 v44, v2
	v_mov_b32_e32 v45, v2
	v_mov_b32_e32 v50, v2
	v_mov_b32_e32 v51, v2
	v_mov_b32_e32 v52, v2
	v_mov_b32_e32 v53, v2
	v_mov_b32_e32 v14, v2
	v_mov_b32_e32 v15, v2
	v_mov_b32_e32 v16, v2
	v_mov_b32_e32 v17, v2
	v_mov_b32_e32 v22, v2
	v_mov_b32_e32 v23, v2
	v_mov_b32_e32 v24, v2
	v_mov_b32_e32 v25, v2
	v_mov_b32_e32 v30, v2
	v_mov_b32_e32 v31, v2
	v_mov_b32_e32 v32, v2
	v_mov_b32_e32 v33, v2
	v_mov_b32_e32 v38, v2
	v_mov_b32_e32 v39, v2
	v_mov_b32_e32 v40, v2
	v_mov_b32_e32 v41, v2
	v_mov_b32_e32 v46, v2
	v_mov_b32_e32 v47, v2
	v_mov_b32_e32 v48, v2
	v_mov_b32_e32 v49, v2
	v_mov_b32_e32 v54, v2
	v_mov_b32_e32 v55, v2
	v_mov_b32_e32 v56, v2
	v_mov_b32_e32 v57, v2
	v_mov_b32_e32 v58, v2
	v_mov_b32_e32 v59, v2
	v_mov_b32_e32 v60, v2
	v_mov_b32_e32 v61, v2
	v_mov_b32_e32 v62, v2
	v_mov_b32_e32 v63, v2
	v_mov_b32_e32 v64, v2
	v_mov_b32_e32 v65, v2
	v_mov_b32_e32 v66, v2
	v_mov_b32_e32 v67, v2
	v_mov_b32_e32 v68, v2
	v_mov_b32_e32 v69, v2
	v_mov_b32_e32 v70, v2
	v_mov_b32_e32 v71, v2
	v_mov_b32_e32 v72, v2
	v_mov_b32_e32 v73, v2
	v_mov_b32_e32 v74, v2
	v_mov_b32_e32 v75, v2
	v_mov_b32_e32 v76, v2
	v_mov_b32_e32 v77, v2
	v_mov_b32_e32 v82, v2
	v_mov_b32_e32 v83, v2
	v_mov_b32_e32 v84, v2
	v_mov_b32_e32 v85, v2
	v_mov_b32_e32 v90, v2
	v_mov_b32_e32 v91, v2
	v_mov_b32_e32 v92, v2
	v_mov_b32_e32 v93, v2
	v_mov_b32_e32 v98, v2
	v_mov_b32_e32 v99, v2
	v_mov_b32_e32 v100, v2
	v_mov_b32_e32 v101, v2
	v_mov_b32_e32 v106, v2
	v_mov_b32_e32 v107, v2
	v_mov_b32_e32 v108, v2
	v_mov_b32_e32 v109, v2
	v_mov_b32_e32 v114, v2
	v_mov_b32_e32 v115, v2
	v_mov_b32_e32 v116, v2
	v_mov_b32_e32 v117, v2
	v_mov_b32_e32 v78, v2
	v_mov_b32_e32 v79, v2
	v_mov_b32_e32 v80, v2
	v_mov_b32_e32 v81, v2
	v_mov_b32_e32 v86, v2
	v_mov_b32_e32 v87, v2
	v_mov_b32_e32 v88, v2
	v_mov_b32_e32 v89, v2
	v_mov_b32_e32 v94, v2
	v_mov_b32_e32 v95, v2
	v_mov_b32_e32 v96, v2
	v_mov_b32_e32 v97, v2
	v_mov_b32_e32 v102, v2
	v_mov_b32_e32 v103, v2
	v_mov_b32_e32 v104, v2
	v_mov_b32_e32 v105, v2
	v_mov_b32_e32 v110, v2
	v_mov_b32_e32 v111, v2
	v_mov_b32_e32 v112, v2
	v_mov_b32_e32 v113, v2
	v_mov_b32_e32 v118, v2
	v_mov_b32_e32 v119, v2
	v_mov_b32_e32 v120, v2
	v_mov_b32_e32 v121, v2
	v_mov_b32_e32 v122, v2
	v_mov_b32_e32 v123, v2
	v_mov_b32_e32 v124, v2
	v_mov_b32_e32 v125, v2
	v_mov_b32_e32 v126, v2
	v_mov_b32_e32 v127, v2
	v_mov_b32_e32 v128, v2
	v_mov_b32_e32 v129, v2
	.p2align	6
	s_nop 0
	s_nop 0
	s_nop 0
	s_nop 0
	s_nop 0
	s_nop 0
